# SWA Q/sink prefetch per task; UP: peeled first K-iteration of non-first units lets previous unit's 8 epilogue stores stay in flight (vmcnt 16)
# baseline (speedup 1.0000x reference)
.LBB0_148:
	s_ashr_i32 s13, s24, 31
	s_ashr_i32 s12, s24, 2
	s_lshr_b32 s13, s13, 26
	s_add_i32 s13, s12, s13
	s_ashr_i32 s22, s13, 6
	s_andn2_b32 s13, s13, 63
	s_sub_i32 s13, s12, s13
	s_and_b32 s25, s24, 3
	s_lshl_b32 s12, s13, 8
	s_cmp_eq_u32 s13, 0
	s_cselect_b32 s30, 0x80, 0
	s_ashr_i32 s23, s22, 31
	s_lshl_b64 s[22:23], s[22:23], 14
	s_ashr_i32 s13, s12, 31
	s_lshl_b32 s31, s25, 6
	s_barrier
	s_add_i32 s46, s12, s19
	s_ashr_i32 s47, s46, 31
	s_add_u32 s46, s22, s46
	s_addc_u32 s47, s23, s47
	v_mov_b32_e32 v243, s47
	v_or_b32_e32 v242, s46, v66
	v_lshlrev_b64 v[242:243], 11, v[242:243]
	v_lshl_add_u64 v[248:249], v[68:69], 0, v[242:243]
	s_mul_i32 s46, s25, 0x180
	s_mov_b32 s47, 0
	v_lshl_add_u64 v[248:249], v[248:249], 0, s[46:47]
	global_load_dwordx4 v[50:53], v[248:249], off nt
	global_load_dwordx4 v[54:57], v[248:249], off offset:32 nt
	global_load_dwordx4 v[58:61], v[248:249], off offset:64 nt
	global_load_dwordx4 v[62:65], v[248:249], off offset:96 nt
	s_mul_i32 s46, s25, 12
	s_add_u32 s46, s4, s46
	s_addc_u32 s47, s5, 0
	global_load_dword v245, v135, s[46:47] offset:-96
	global_load_dword v246, v135, s[46:47] offset:-92
	global_load_dword v247, v135, s[46:47] offset:-88
	s_add_u32 s44, s22, s12
	s_addc_u32 s45, s23, s13
	s_lshl_b64 s[44:45], s[44:45], 9
	s_add_u32 s37, s82, s44
	s_addc_u32 s41, s83, s45
	s_lshl_b32 s44, s31, 1
	s_add_u32 s44, s37, s44
	s_addc_u32 s45, s41, 0
	v_mov_b32_e32 v75, v135
	v_lshl_add_u64 v[2:3], s[44:45], 0, v[74:75]
	s_mov_b64 s[44:45], 0xa1f0000
	v_lshl_add_u64 v[2:3], v[2:3], 0, s[44:45]
	v_ashrrev_i32_e32 v134, 3, v130
	v_lshlrev_b64 v[6:7], 9, v[134:135]
	v_lshl_add_u64 v[6:7], v[2:3], 0, v[6:7]
	v_mad_u32_u24 v226, v134, s29, v70
	s_mov_b64 s[44:45], 0x8000
	global_load_dwordx4 v[178:181], v[6:7], off
	v_lshl_add_u64 v[6:7], v[6:7], 0, s[44:45]
	global_load_dwordx4 v[182:185], v[6:7], off
	v_lshl_add_u64 v[6:7], v[6:7], 0, s[44:45]
	global_load_dwordx4 v[186:189], v[6:7], off
	v_lshl_add_u64 v[6:7], v[6:7], 0, s[44:45]
	global_load_dwordx4 v[190:193], v[6:7], off
	v_lshl_add_u64 v[6:7], v[6:7], 0, s[44:45]
	global_load_dwordx4 v[194:197], v[6:7], off
	v_lshl_add_u64 v[6:7], v[6:7], 0, s[44:45]
	global_load_dwordx4 v[198:201], v[6:7], off
	s_lshl_b32 s31, s31, 16
	s_add_u32 s31, s82, s31
	s_addc_u32 s37, s83, 0
	s_lshl_b64 s[44:45], s[22:23], 1
	s_add_u32 s31, s31, s44
	s_addc_u32 s37, s37, s45
	s_lshl_b64 s[44:45], s[12:13], 1
	s_add_u32 s13, s31, s44
	s_addc_u32 s31, s37, s45
	s_add_u32 s44, s13, 0xb1fff00
	s_addc_u32 s45, s31, 0
	s_movk_i32 s46, 0xfe80
	s_movk_i32 s47, 0x308
	s_mov_b32 s50, 0xd800
	v_mov_b32_e32 v240, v130
	v_mul_hi_i32 v241, v240, s17
	v_ashrrev_i32_e32 v241, 4, v241
	v_lshlrev_b32_e32 v242, 2, v240
	v_mad_i32_i24 v242, v241, s46, v242
	v_lshlrev_b32_e32 v243, 16, v241
	v_lshl_add_u32 v243, v242, 1, v243
	global_load_dwordx2 v[202:203], v243, s[44:45]
	v_lshl_add_u32 v244, v242, 1, s50
	v_mad_u32_u24 v228, v241, s47, v244
	v_add_u32_e32 v240, 0x200, v130
	v_mul_hi_i32 v241, v240, s17
	v_ashrrev_i32_e32 v241, 4, v241
	v_lshlrev_b32_e32 v242, 2, v240
	v_mad_i32_i24 v242, v241, s46, v242
	v_lshlrev_b32_e32 v243, 16, v241
	v_lshl_add_u32 v243, v242, 1, v243
	global_load_dwordx2 v[204:205], v243, s[44:45]
	v_lshl_add_u32 v244, v242, 1, s50
	v_mad_u32_u24 v229, v241, s47, v244
	v_add_u32_e32 v240, 0x400, v130
	v_mul_hi_i32 v241, v240, s17
	v_ashrrev_i32_e32 v241, 4, v241
	v_lshlrev_b32_e32 v242, 2, v240
	v_mad_i32_i24 v242, v241, s46, v242
	v_lshlrev_b32_e32 v243, 16, v241
	v_lshl_add_u32 v243, v242, 1, v243
	global_load_dwordx2 v[206:207], v243, s[44:45]
	v_lshl_add_u32 v244, v242, 1, s50
	v_mad_u32_u24 v230, v241, s47, v244
	v_add_u32_e32 v240, 0x600, v130
	v_mul_hi_i32 v241, v240, s17
	v_ashrrev_i32_e32 v241, 4, v241
	v_lshlrev_b32_e32 v242, 2, v240
	v_mad_i32_i24 v242, v241, s46, v242
	v_lshlrev_b32_e32 v243, 16, v241
	v_lshl_add_u32 v243, v242, 1, v243
	global_load_dwordx2 v[208:209], v243, s[44:45]
	v_lshl_add_u32 v244, v242, 1, s50
	v_mad_u32_u24 v231, v241, s47, v244
	v_add_u32_e32 v240, 0x800, v130
	v_mul_hi_i32 v241, v240, s17
	v_ashrrev_i32_e32 v241, 4, v241
	v_lshlrev_b32_e32 v242, 2, v240
	v_mad_i32_i24 v242, v241, s46, v242
	v_lshlrev_b32_e32 v243, 16, v241
	v_lshl_add_u32 v243, v242, 1, v243
	global_load_dwordx2 v[210:211], v243, s[44:45]
	v_lshl_add_u32 v244, v242, 1, s50
	v_mad_u32_u24 v232, v241, s47, v244
	v_add_u32_e32 v240, 0xa00, v130
	v_mul_hi_i32 v241, v240, s17
	v_ashrrev_i32_e32 v241, 4, v241
	v_lshlrev_b32_e32 v242, 2, v240
	v_mad_i32_i24 v242, v241, s46, v242
	v_lshlrev_b32_e32 v243, 16, v241
	v_lshl_add_u32 v243, v242, 1, v243
	global_load_dwordx2 v[212:213], v243, s[44:45]
	v_lshl_add_u32 v244, v242, 1, s50
	v_mad_u32_u24 v233, v241, s47, v244
	v_add_u32_e32 v240, 0xc00, v130
	v_mul_hi_i32 v241, v240, s17
	v_ashrrev_i32_e32 v241, 4, v241
	v_lshlrev_b32_e32 v242, 2, v240
	v_mad_i32_i24 v242, v241, s46, v242
	v_lshlrev_b32_e32 v243, 16, v241
	v_lshl_add_u32 v243, v242, 1, v243
	global_load_dwordx2 v[214:215], v243, s[44:45]
	v_lshl_add_u32 v244, v242, 1, s50
	v_mad_u32_u24 v234, v241, s47, v244
	v_add_u32_e32 v240, 0xe00, v130
	v_mul_hi_i32 v241, v240, s17
	v_ashrrev_i32_e32 v241, 4, v241
	v_lshlrev_b32_e32 v242, 2, v240
	v_mad_i32_i24 v242, v241, s46, v242
	v_lshlrev_b32_e32 v243, 16, v241
	v_lshl_add_u32 v243, v242, 1, v243
	global_load_dwordx2 v[216:217], v243, s[44:45]
	v_lshl_add_u32 v244, v242, 1, s50
	v_mad_u32_u24 v235, v241, s47, v244
	v_add_u32_e32 v240, 0x1000, v130
	v_mul_hi_i32 v241, v240, s17
	v_ashrrev_i32_e32 v241, 4, v241
	v_lshlrev_b32_e32 v242, 2, v240
	v_mad_i32_i24 v242, v241, s46, v242
	v_lshlrev_b32_e32 v243, 16, v241
	v_lshl_add_u32 v243, v242, 1, v243
	global_load_dwordx2 v[218:219], v243, s[44:45]
	v_lshl_add_u32 v244, v242, 1, s50
	v_mad_u32_u24 v236, v241, s47, v244
	v_add_u32_e32 v240, 0x1200, v130
	v_mul_hi_i32 v241, v240, s17
	v_ashrrev_i32_e32 v241, 4, v241
	v_lshlrev_b32_e32 v242, 2, v240
	v_mad_i32_i24 v242, v241, s46, v242
	v_lshlrev_b32_e32 v243, 16, v241
	v_lshl_add_u32 v243, v242, 1, v243
	global_load_dwordx2 v[220:221], v243, s[44:45]
	v_lshl_add_u32 v244, v242, 1, s50
	v_mad_u32_u24 v237, v241, s47, v244
	v_add_u32_e32 v240, 0x1400, v130
	v_mul_hi_i32 v241, v240, s17
	v_ashrrev_i32_e32 v241, 4, v241
	v_lshlrev_b32_e32 v242, 2, v240
	v_mad_i32_i24 v242, v241, s46, v242
	v_lshlrev_b32_e32 v243, 16, v241
	v_lshl_add_u32 v243, v242, 1, v243
	global_load_dwordx2 v[222:223], v243, s[44:45]
	v_lshl_add_u32 v244, v242, 1, s50
	v_mad_u32_u24 v238, v241, s47, v244
	v_add_u32_e32 v240, 0x1600, v130
	v_mul_hi_i32 v241, v240, s17
	v_ashrrev_i32_e32 v241, 4, v241
	v_lshlrev_b32_e32 v242, 2, v240
	v_mad_i32_i24 v242, v241, s46, v242
	v_lshlrev_b32_e32 v243, 16, v241
	v_lshl_add_u32 v243, v242, 1, v243
	global_load_dwordx2 v[224:225], v243, s[44:45]
	v_lshl_add_u32 v244, v242, 1, s50
	v_mad_u32_u24 v239, v241, s47, v244
	s_waitcnt vmcnt(17)
	ds_write_b128 v226, v[178:181]
	s_waitcnt vmcnt(16)
	ds_write_b128 v226, v[182:185] offset:9216
	s_waitcnt vmcnt(15)
	ds_write_b128 v226, v[186:189] offset:18432
	s_waitcnt vmcnt(14)
	ds_write_b128 v226, v[190:193] offset:27648
	s_waitcnt vmcnt(13)
	ds_write_b128 v226, v[194:197] offset:36864
	s_waitcnt vmcnt(12)
	ds_write_b128 v226, v[198:201] offset:46080
	s_waitcnt vmcnt(11)
	ds_write_b64 v228, v[202:203]
	s_waitcnt vmcnt(10)
	ds_write_b64 v229, v[204:205]
	s_waitcnt vmcnt(9)
	ds_write_b64 v230, v[206:207]
	s_waitcnt vmcnt(8)
	ds_write_b64 v231, v[208:209]
	s_waitcnt vmcnt(7)
	ds_write_b64 v232, v[210:211]
	s_waitcnt vmcnt(6)
	ds_write_b64 v233, v[212:213]
	s_waitcnt vmcnt(5)
	ds_write_b64 v234, v[214:215]
	s_waitcnt vmcnt(4)
	ds_write_b64 v235, v[216:217]
	s_waitcnt vmcnt(3)
	ds_write_b64 v236, v[218:219]
	s_waitcnt vmcnt(2)
	ds_write_b64 v237, v[220:221]
	s_waitcnt vmcnt(1)
	ds_write_b64 v238, v[222:223]
	s_waitcnt vmcnt(0)
	ds_write_b64 v239, v[224:225]
.LBB0_158:
	s_and_b32 s13, s21, 3
	s_add_i32 s12, s12, s19
	s_mul_i32 s26, s13, 0x600
	s_ashr_i32 s13, s12, 31
	s_add_u32 s22, s22, s12
	s_addc_u32 s13, s23, s13
	v_mov_b32_e32 v3, s13
	s_sub_i32 s13, 0x80, s12
	s_ashr_i32 s13, s13, 5
	s_cmpk_lt_i32 s12, 0x80
	v_or_b32_e32 v2, s22, v66
	s_cselect_b32 s22, s13, 0
	s_cmp_gt_i32 s22, 4
	s_cselect_b64 s[12:13], -1, 0
	s_add_i32 s23, s38, s22
	v_lshlrev_b64 v[2:3], 11, v[2:3]
	s_mul_i32 s27, s23, 0x1200
	v_lshl_add_u64 v[76:77], v[68:69], 0, v[2:3]
	v_lshl_add_u64 v[78:79], v[72:73], 0, v[2:3]
	s_add_i32 s31, s22, -1
	v_add_u32_e32 v75, s27, v71
	s_lshl_b32 s27, s22, 5
	v_add_u32_e32 v2, s26, v81
	s_lshl_b32 s22, s22, 7
	v_subrev_u32_e32 v85, s22, v2
	s_lshl_b32 s22, s23, 6
	s_mul_i32 s25, s25, 3
	s_mov_b32 s30, 0
	v_subrev_u32_e32 v84, s27, v80
	v_add_u32_e32 v86, s22, v82
	v_add_u32_e32 v87, s22, v83
	s_waitcnt lgkmcnt(0)
	global_load_dwordx4 v[178:181], v[248:249], off offset:128 nt
	global_load_dwordx4 v[182:185], v[248:249], off offset:160 nt
	global_load_dwordx4 v[186:189], v[248:249], off offset:192 nt
	global_load_dwordx4 v[190:193], v[248:249], off offset:224 nt
	global_load_dwordx4 v[194:197], v[248:249], off offset:256 nt
	global_load_dwordx4 v[198:201], v[248:249], off offset:288 nt
	global_load_dwordx4 v[202:205], v[248:249], off offset:320 nt
	global_load_dwordx4 v[206:209], v[248:249], off offset:352 nt
	s_barrier
	s_branch .LBB0_161

.LBB0_163:
	s_add_i32 s22, s30, s25
	v_mov_b32_e32 v17, 0
	s_lshl_b32 s37, s22, 6
	s_andn2_b64 vcc, exec, s[26:27]
	v_mov_b32_e32 v16, v17
	v_mov_b32_e32 v15, v17
	v_mov_b32_e32 v14, v17
	v_mov_b32_e32 v13, v17
	v_mov_b32_e32 v12, v17
	v_mov_b32_e32 v11, v17
	v_mov_b32_e32 v10, v17
	v_mov_b32_e32 v9, v17
	v_mov_b32_e32 v8, v17
	v_mov_b32_e32 v7, v17
	v_mov_b32_e32 v6, v17
	v_mov_b32_e32 v5, v17
	v_mov_b32_e32 v4, v17
	v_mov_b32_e32 v3, v17
	v_mov_b32_e32 v2, v17
	v_mov_b32_e32 v33, v17
	v_mov_b32_e32 v32, v17
	v_mov_b32_e32 v31, v17
	v_mov_b32_e32 v30, v17
	v_mov_b32_e32 v29, v17
	v_mov_b32_e32 v28, v17
	v_mov_b32_e32 v27, v17
	v_mov_b32_e32 v26, v17
	v_mov_b32_e32 v25, v17
	v_mov_b32_e32 v24, v17
	v_mov_b32_e32 v23, v17
	v_mov_b32_e32 v22, v17
	v_mov_b32_e32 v21, v17
	v_mov_b32_e32 v20, v17
	v_mov_b32_e32 v19, v17
	v_mov_b32_e32 v18, v17
	v_mov_b32_e32 v35, v67
	s_cbranch_vccnz .LBB0_160
	s_mov_b32 s23, s61
	s_lshl_b32 s60, s37, 1
	s_lshl_b64 s[22:23], s[22:23], 2
	v_lshl_add_u64 v[2:3], v[76:77], 0, s[60:61]
	s_add_u32 s22, s4, s22
	s_addc_u32 s23, s5, s23
	v_cmp_lt_i32_e32 vcc, v177, v171
	v_mov_b32_e32 v2, 0
	v_mov_b32_e32 v88, v87
	v_cndmask_b32_e32 v3, v170, v177, vcc
	v_mov_b32_e32 v89, v86
	v_mov_b32_e32 v90, v85
	v_mov_b32_e32 v91, v84
	v_mov_b32_e32 v92, v75
	s_mov_b32 s26, s31
	v_mov_b32_e32 v94, v67
	v_lshlrev_b32_e32 v93, 2, v3
	v_mov_b32_e32 v3, v2
	v_mov_b32_e32 v4, v2
	v_mov_b32_e32 v5, v2
	v_mov_b32_e32 v6, v2
	v_mov_b32_e32 v7, v2
	v_mov_b32_e32 v8, v2
	v_mov_b32_e32 v9, v2
	v_mov_b32_e32 v10, v2
	v_mov_b32_e32 v11, v2
	v_mov_b32_e32 v12, v2
	v_mov_b32_e32 v13, v2
	v_mov_b32_e32 v14, v2
	v_mov_b32_e32 v15, v2
	v_mov_b32_e32 v16, v2
	v_mov_b32_e32 v17, v2
	v_mov_b32_e32 v18, v2
	v_mov_b32_e32 v19, v2
	v_mov_b32_e32 v20, v2
	v_mov_b32_e32 v21, v2
	v_mov_b32_e32 v22, v2
	v_mov_b32_e32 v23, v2
	v_mov_b32_e32 v24, v2
	v_mov_b32_e32 v25, v2
	v_mov_b32_e32 v26, v2
	v_mov_b32_e32 v27, v2
	v_mov_b32_e32 v28, v2
	v_mov_b32_e32 v29, v2
	v_mov_b32_e32 v30, v2
	v_mov_b32_e32 v31, v2
	v_mov_b32_e32 v32, v2
	s_cmp_lg_u32 s30, 0
	s_cbranch_scc1 .Lqp_h1
	v_mul_f32_e32 v95, 0x3fb8aa3b, v245
	s_branch .Lqp_done
.Lqp_h1:
	s_cmp_lg_u32 s30, 1
	s_cbranch_scc1 .Lqp_h2
	s_waitcnt vmcnt(16)
	v_mov_b32_e32 v50, v178
	v_mov_b32_e32 v51, v179
	v_mov_b32_e32 v52, v180
	v_mov_b32_e32 v53, v181
	v_mov_b32_e32 v54, v182
	v_mov_b32_e32 v55, v183
	v_mov_b32_e32 v56, v184
	v_mov_b32_e32 v57, v185
	v_mov_b32_e32 v58, v186
	v_mov_b32_e32 v59, v187
	v_mov_b32_e32 v60, v188
	v_mov_b32_e32 v61, v189
	v_mov_b32_e32 v62, v190
	v_mov_b32_e32 v63, v191
	v_mov_b32_e32 v64, v192
	v_mov_b32_e32 v65, v193
	v_mul_f32_e32 v95, 0x3fb8aa3b, v246
	s_branch .Lqp_done
.Lqp_h2:
	s_waitcnt vmcnt(32)
	v_mov_b32_e32 v50, v194
	v_mov_b32_e32 v51, v195
	v_mov_b32_e32 v52, v196
	v_mov_b32_e32 v53, v197
	v_mov_b32_e32 v54, v198
	v_mov_b32_e32 v55, v199
	v_mov_b32_e32 v56, v200
	v_mov_b32_e32 v57, v201
	v_mov_b32_e32 v58, v202
	v_mov_b32_e32 v59, v203
	v_mov_b32_e32 v60, v204
	v_mov_b32_e32 v61, v205
	v_mov_b32_e32 v62, v206
	v_mov_b32_e32 v63, v207
	v_mov_b32_e32 v64, v208
	v_mov_b32_e32 v65, v209
	v_mul_f32_e32 v95, 0x3fb8aa3b, v247
.Lqp_done:
	v_mov_b32_e32 v33, v2
.LBB0_165:
	v_add_u32_e32 v100, 0, v92
	ds_read_b128 v[34:37], v100
	ds_read_b128 v[96:99], v100 offset:32
	s_waitcnt lgkmcnt(1)
	v_mfma_f32_32x32x16_bf16 v[34:49], v[34:37], v[50:53], 0
	s_waitcnt lgkmcnt(0)
	v_mfma_f32_32x32x16_bf16 v[34:49], v[96:99], v[54:57], v[34:49]
	ds_read_b128 v[96:99], v100 offset:64
	s_waitcnt lgkmcnt(0)
	v_mfma_f32_32x32x16_bf16 v[34:49], v[96:99], v[58:61], v[34:49]
	ds_read_b128 v[96:99], v100 offset:96
	s_waitcnt lgkmcnt(0)
	v_mfma_f32_32x32x16_bf16 v[34:49], v[96:99], v[62:65], v[34:49]
	v_add_u32_e32 v98, 0x19b94, v90
	ds_read_b32 v112, v98 offset:108
	ds_read_b32 v113, v98 offset:104
	ds_read_b32 v114, v98 offset:100
	ds_read_b32 v115, v98 offset:96
	ds_read_b32 v116, v98 offset:76
	ds_read_b32 v117, v98 offset:72
	ds_read_b32 v118, v98 offset:68
	ds_read_b32 v119, v98 offset:64
	ds_read_b32 v120, v98 offset:44
	ds_read_b32 v121, v98 offset:40
	ds_read_b32 v122, v98 offset:36
	ds_read_b32 v123, v98 offset:32
	ds_read_b32 v124, v98 offset:12
	ds_read_b32 v125, v98 offset:8
	ds_read_b32 v126, v98 offset:4
	ds_read_b32 v127, v98
	v_mov_b32_e32 v128, 0xf149f2ca
	v_add_u32_e32 v129, 27, v91
	s_waitcnt lgkmcnt(0)
	v_cmp_gt_u32_e32 vcc, s49, v129
	v_add_f32_e32 v112, v34, v112
	v_add_u32_e32 v129, 26, v91
	v_cndmask_b32_e32 v97, v128, v112, vcc
	v_cmp_gt_u32_e32 vcc, s49, v129
	v_add_f32_e32 v113, v35, v113
	v_add_u32_e32 v129, 25, v91
	v_cndmask_b32_e32 v96, v128, v113, vcc
	v_cmp_gt_u32_e32 vcc, s49, v129
	v_add_f32_e32 v114, v36, v114
	v_add_u32_e32 v129, 24, v91
	v_cndmask_b32_e32 v99, v128, v114, vcc
	v_cmp_gt_u32_e32 vcc, s49, v129
	v_add_f32_e32 v115, v37, v115
	v_add_u32_e32 v129, 19, v91
	v_cndmask_b32_e32 v35, v128, v115, vcc
	v_cmp_gt_u32_e32 vcc, s49, v129
	v_add_f32_e32 v116, v38, v116
	v_add_u32_e32 v129, 18, v91
	v_cndmask_b32_e32 v37, v128, v116, vcc
	v_cmp_gt_u32_e32 vcc, s49, v129
	v_add_f32_e32 v117, v39, v117
	v_add_u32_e32 v129, 17, v91
	v_cndmask_b32_e32 v36, v128, v117, vcc
	v_cmp_gt_u32_e32 vcc, s49, v129
	v_add_f32_e32 v118, v40, v118
	v_add_u32_e32 v129, 16, v91
	v_cndmask_b32_e32 v100, v128, v118, vcc
	v_cmp_gt_u32_e32 vcc, s49, v129
	v_add_f32_e32 v119, v41, v119
	v_add_u32_e32 v129, 11, v91
	v_cndmask_b32_e32 v39, v128, v119, vcc
	v_cmp_gt_u32_e32 vcc, s49, v129
	v_add_f32_e32 v120, v42, v120
	v_add_u32_e32 v129, 10, v91
	v_cndmask_b32_e32 v41, v128, v120, vcc
	v_cmp_gt_u32_e32 vcc, s49, v129
	v_add_f32_e32 v121, v43, v121
	v_add_u32_e32 v129, 9, v91
	v_cndmask_b32_e32 v40, v128, v121, vcc
	v_cmp_gt_u32_e32 vcc, s49, v129
	v_add_f32_e32 v122, v44, v122
	v_add_u32_e32 v129, 8, v91
	v_cndmask_b32_e32 v43, v128, v122, vcc
	v_cmp_gt_u32_e32 vcc, s49, v129
	v_add_f32_e32 v123, v45, v123
	v_add_u32_e32 v129, 3, v91
	v_cndmask_b32_e32 v42, v128, v123, vcc
	v_cmp_gt_u32_e32 vcc, s49, v129
	v_add_f32_e32 v124, v46, v124
	v_add_u32_e32 v129, 2, v91
	v_cndmask_b32_e32 v45, v128, v124, vcc
	v_cmp_gt_u32_e32 vcc, s49, v129
	v_add_f32_e32 v125, v47, v125
	v_add_u32_e32 v129, 1, v91
	v_cndmask_b32_e32 v44, v128, v125, vcc
	v_cmp_gt_u32_e32 vcc, s49, v129
	v_add_f32_e32 v126, v48, v126
	v_mov_b32_e32 v129, v91
	v_cndmask_b32_e32 v46, v128, v126, vcc
	v_cmp_gt_u32_e32 vcc, s49, v129
	v_add_f32_e32 v127, v49, v127
	s_nop 0
	v_cndmask_b32_e32 v38, v128, v127, vcc
	v_max_f32_e32 v34, v96, v96
	v_max_f32_e32 v47, v97, v97
	v_max_f32_e32 v34, v47, v34
	v_max3_f32 v34, v34, v99, v35
	v_max3_f32 v34, v34, v37, v36
	v_max3_f32 v34, v34, v100, v39
	v_max3_f32 v34, v34, v41, v40
	v_max3_f32 v34, v34, v43, v42
	v_max3_f32 v34, v34, v45, v44
	v_max3_f32 v34, v34, v46, v38
	ds_bpermute_b32 v47, v93, v34
	v_add_u32_e32 v111, 0, v88
	s_add_i32 s26, s26, 1
	v_add_u32_e32 v92, 0x1200, v92
	v_subrev_u32_e32 v91, 32, v91
	s_waitcnt lgkmcnt(0)
	v_max3_f32 v34, v95, v34, v47
	v_sub_f32_e32 v36, v36, v34
	v_exp_f32_e32 v103, v36
	v_sub_f32_e32 v36, v100, v34
	v_exp_f32_e32 v100, v36
	v_sub_f32_e32 v36, v39, v34
	v_exp_f32_e32 v104, v36
	v_sub_f32_e32 v36, v41, v34
	v_exp_f32_e32 v105, v36
	v_sub_f32_e32 v36, v40, v34
	v_exp_f32_e32 v106, v36
	v_sub_f32_e32 v36, v43, v34
	v_exp_f32_e32 v107, v36
	v_sub_f32_e32 v36, v42, v34
	v_sub_f32_e32 v48, v97, v34
	v_sub_f32_e32 v37, v37, v34
	v_exp_f32_e32 v108, v36
	v_sub_f32_e32 v36, v45, v34
	v_sub_f32_e32 v47, v95, v34
	v_exp_f32_e32 v95, v48
	v_sub_f32_e32 v48, v99, v34
	v_exp_f32_e32 v102, v37
	v_exp_f32_e32 v109, v36
	v_sub_f32_e32 v36, v44, v34
	v_add_u32_e32 v37, 0, v89
	v_sub_f32_e32 v49, v96, v34
	v_exp_f32_e32 v101, v48
	v_exp_f32_e32 v48, v47
	v_exp_f32_e32 v110, v36
	v_sub_f32_e32 v36, v46, v34
	ds_read2_b64 v[44:47], v37 offset1:2
	ds_read2_b64 v[96:99], v111 offset1:2
	v_sub_f32_e32 v35, v35, v34
	v_exp_f32_e32 v49, v49
	v_exp_f32_e32 v35, v35
	v_cvt_pk_bf16_f32 v42, v102, v103
	v_cvt_pk_bf16_f32 v43, v100, v104
	v_pk_mul_f32 v[32:33], v[32:33], v[48:49] op_sel_hi:[1,0]
	v_pk_mul_f32 v[30:31], v[30:31], v[48:49] op_sel_hi:[1,0]
	v_cvt_pk_bf16_f32 v40, v95, v49
	v_cvt_pk_bf16_f32 v41, v101, v35
	v_pk_mul_f32 v[16:17], v[16:17], v[48:49] op_sel_hi:[1,0]
	v_pk_mul_f32 v[14:15], v[14:15], v[48:49] op_sel_hi:[1,0]
	v_pk_mul_f32 v[12:13], v[12:13], v[48:49] op_sel_hi:[1,0]
	v_pk_mul_f32 v[10:11], v[10:11], v[48:49] op_sel_hi:[1,0]
	v_pk_mul_f32 v[8:9], v[8:9], v[48:49] op_sel_hi:[1,0]
	v_pk_mul_f32 v[6:7], v[6:7], v[48:49] op_sel_hi:[1,0]
	v_pk_mul_f32 v[4:5], v[4:5], v[48:49] op_sel_hi:[1,0]
	v_pk_mul_f32 v[2:3], v[2:3], v[48:49] op_sel_hi:[1,0]
	v_pk_mul_f32 v[28:29], v[28:29], v[48:49] op_sel_hi:[1,0]
	v_pk_mul_f32 v[26:27], v[26:27], v[48:49] op_sel_hi:[1,0]
	v_pk_mul_f32 v[24:25], v[24:25], v[48:49] op_sel_hi:[1,0]
	v_pk_mul_f32 v[22:23], v[22:23], v[48:49] op_sel_hi:[1,0]
	v_pk_mul_f32 v[20:21], v[20:21], v[48:49] op_sel_hi:[1,0]
	v_pk_mul_f32 v[18:19], v[18:19], v[48:49] op_sel_hi:[1,0]
	s_waitcnt lgkmcnt(1)
	v_mfma_f32_32x32x16_bf16 v[2:17], v[44:47], v[40:43], v[2:17]
	ds_read2_b64 v[44:47], v37 offset0:4 offset1:6
	v_cvt_pk_bf16_f32 v37, v107, v108
	v_add_u32_e32 v90, 0xffffff80, v90
	v_add_u32_e32 v89, 64, v89
	s_cmp_lt_i32 s26, 4
	v_add_u32_e32 v88, 64, v88
	s_waitcnt lgkmcnt(1)
	v_mfma_f32_32x32x16_bf16 v[18:33], v[96:99], v[40:43], v[18:33]
	ds_read2_b64 v[40:43], v111 offset0:4 offset1:6
	v_exp_f32_e32 v96, v36
	v_sub_f32_e32 v36, v38, v34
	v_exp_f32_e32 v97, v36
	v_cvt_pk_bf16_f32 v36, v105, v106
	v_cvt_pk_bf16_f32 v38, v109, v110
	v_cvt_pk_bf16_f32 v39, v96, v97
	s_waitcnt lgkmcnt(1)
	s_nop 0
	v_mfma_f32_32x32x16_bf16 v[2:17], v[44:47], v[36:39], v[2:17]
	s_waitcnt lgkmcnt(0)
	v_mfma_f32_32x32x16_bf16 v[18:33], v[40:43], v[36:39], v[18:33]
	v_add_f32_e32 v36, 0, v95
	v_add_f32_e32 v36, v49, v36
	v_add_f32_e32 v36, v101, v36
	v_add_f32_e32 v35, v35, v36
	v_add_f32_e32 v35, v102, v35
	v_add_f32_e32 v35, v103, v35
	v_add_f32_e32 v35, v100, v35
	v_add_f32_e32 v35, v104, v35
	v_add_f32_e32 v35, v105, v35
	v_add_f32_e32 v35, v106, v35
	v_add_f32_e32 v35, v107, v35
	v_add_f32_e32 v35, v108, v35
	v_add_f32_e32 v35, v109, v35
	v_add_f32_e32 v35, v110, v35
	v_add_f32_e32 v35, v96, v35
	v_add_f32_e32 v35, v97, v35
	v_fmac_f32_e32 v35, v94, v48
	s_cbranch_scc0 .LBB0_159
	v_mov_b32_e32 v95, v34
	v_mov_b32_e32 v94, v35
	s_branch .LBB0_165

.LBB0_277:
	s_lshl_b32 s12, s12, 5
	s_and_b32 s24, s12, 0x60
	s_add_i32 m0, s50, 0x18000
	v_lshl_add_u64 v[8:9], v[8:9], 0, s[66:67]
	s_lshl_b32 s21, s7, 13
	s_lshl_b32 s25, s24, 7
	s_waitcnt vmcnt(2)
	s_barrier
	global_load_lds_dwordx4 v[8:9], off
	v_lshl_add_u64 v[6:7], v[6:7], 0, s[66:67]
	s_add_i32 m0, s50, 0x1a000
	s_add_i32 s19, s50, 0x8000
	s_add_i32 s60, s50, 0xa000
	global_load_lds_dwordx4 v[6:7], off
	v_lshl_add_u64 v[2:3], v[2:3], 0, s[66:67]
	s_mov_b32 m0, s19
	s_add_u32 s12, s26, 0x40080
	global_load_lds_dwordx4 v[2:3], off
	v_lshl_add_u64 v[2:3], v[4:5], 0, s[66:67]
	s_mov_b32 m0, s60
	s_addc_u32 s13, s27, 0
	global_load_lds_dwordx4 v[2:3], off
	s_add_i32 m0, s50, 0x1c000
	v_lshl_add_u64 v[2:3], s[12:13], 0, v[134:135]
	global_load_lds_dwordx4 v[2:3], off
	v_lshl_add_u64 v[2:3], s[12:13], 0, v[132:133]
	s_add_i32 m0, s50, 0x1e000
	v_mov_b32_e32 v149, v135
	global_load_lds_dwordx4 v[2:3], off
	v_and_b32_e32 v2, 15, v130
	v_lshrrev_b32_e32 v3, 1, v130
	v_lshl_or_b32 v131, s7, 6, v2
	v_and_b32_e32 v3, 24, v3
	s_lshl_b32 s7, s7, 8
	v_lshlrev_b32_e32 v4, 1, v3
	s_add_i32 s7, s7, 0
	v_lshl_or_b32 v4, v2, 6, v4
	v_lshlrev_b32_e32 v2, 2, v2
	s_add_i32 s7, s7, 0x20400
	v_and_b32_e32 v5, 32, v2
	v_add_u32_e32 v153, s7, v2
	v_lshlrev_b32_e32 v2, 14, v14
	v_and_b32_e32 v2, 0xffff8000, v2
	v_or_b32_e32 v154, s24, v3
	v_lshl_add_u32 v2, v13, 11, v2
	v_and_b32_e32 v3, 1, v14
	v_lshl_or_b32 v2, v3, 6, v2
	v_lshl_add_u32 v148, v15, 1, v2
	v_lshlrev_b32_e32 v2, 14, v10
	v_and_b32_e32 v2, 0xffff8000, v2
	s_waitcnt vmcnt(6)
	v_lshl_add_u32 v2, v11, 11, v2
	v_and_b32_e32 v3, 1, v10
	v_bitop3_b32 v6, v4, s21, v5 bitop3:0xde
	s_cmpk_lt_u32 s6, 0x100
	v_lshl_or_b32 v2, v3, 6, v2
	v_readlane_b32 s6, v254, 21
	v_bitop3_b32 v152, s25, v4, v5 bitop3:0xf6
	s_cselect_b64 s[92:93], -1, 0
	v_lshl_add_u32 v150, v12, 1, v2
	v_mov_b32_e32 v151, v135
	s_mov_b32 s25, 0
	v_add_u32_e32 v155, 0, v6
	v_readlane_b32 s21, v254, 20
	s_mov_b32 s24, s6
	s_mov_b32 s62, 0
	s_barrier
	v_readlane_b32 s7, v254, 22
	v_writelane_b32 v253, 0, 0
	s_branch .LBB0_280

.LBB0_279:
	v_writelane_b32 v253, 1, 0
	s_andn2_b64 vcc, exec, s[6:7]
	s_mov_b32 s25, s64
	s_mov_b32 s21, s12
	s_mov_b32 s24, s46
	s_mov_b64 s[26:27], s[96:97]
	s_mov_b64 s[22:23], s[94:95]
	s_cbranch_vccz .LBB0_289

.LBB0_282:
	s_ashr_i32 s47, s46, 31
	s_lshl_b64 s[44:45], s[46:47], 19
	s_add_u32 s94, s78, s44
	s_addc_u32 s95, s79, s45
	s_and_b64 s[44:45], s[6:7], exec
	s_cselect_b32 s30, s95, s23
	s_cselect_b32 s37, s94, s22
	s_ashr_i32 s13, s12, 31
	s_lshl_b64 s[44:45], s[12:13], 19
	s_add_u32 s96, s4, s44
	s_addc_u32 s97, s5, s45
	s_and_b64 s[44:45], s[6:7], exec
	s_cselect_b32 s13, s97, s27
	s_cselect_b32 s47, s96, s26
	s_add_u32 s22, s22, 0x40080
	s_addc_u32 s23, s23, 0
	s_add_u32 s56, s26, 0x100
	v_mov_b32_e32 v2, 0
	s_addc_u32 s65, s27, 0
	s_mov_b32 s68, -2
	v_mov_b32_e32 v3, v2
	v_mov_b32_e32 v4, v2
	v_mov_b32_e32 v5, v2
	v_mov_b32_e32 v10, v2
	v_mov_b32_e32 v11, v2
	v_mov_b32_e32 v12, v2
	v_mov_b32_e32 v13, v2
	v_mov_b32_e32 v18, v2
	v_mov_b32_e32 v19, v2
	v_mov_b32_e32 v20, v2
	v_mov_b32_e32 v21, v2
	v_mov_b32_e32 v26, v2
	v_mov_b32_e32 v27, v2
	v_mov_b32_e32 v28, v2
	v_mov_b32_e32 v29, v2
	v_mov_b32_e32 v34, v2
	v_mov_b32_e32 v35, v2
	v_mov_b32_e32 v36, v2
	v_mov_b32_e32 v37, v2
	v_mov_b32_e32 v42, v2
	v_mov_b32_e32 v43, v2
	v_mov_b32_e32 v44, v2
	v_mov_b32_e32 v45, v2
	v_mov_b32_e32 v50, v2
	v_mov_b32_e32 v51, v2
	v_mov_b32_e32 v52, v2
	v_mov_b32_e32 v53, v2
	v_mov_b32_e32 v58, v2
	v_mov_b32_e32 v59, v2
	v_mov_b32_e32 v60, v2
	v_mov_b32_e32 v61, v2
	v_mov_b32_e32 v6, v2
	v_mov_b32_e32 v7, v2
	v_mov_b32_e32 v8, v2
	v_mov_b32_e32 v9, v2
	v_mov_b32_e32 v14, v2
	v_mov_b32_e32 v15, v2
	v_mov_b32_e32 v16, v2
	v_mov_b32_e32 v17, v2
	v_mov_b32_e32 v22, v2
	v_mov_b32_e32 v23, v2
	v_mov_b32_e32 v24, v2
	v_mov_b32_e32 v25, v2
	v_mov_b32_e32 v30, v2
	v_mov_b32_e32 v31, v2
	v_mov_b32_e32 v32, v2
	v_mov_b32_e32 v33, v2
	v_mov_b32_e32 v38, v2
	v_mov_b32_e32 v39, v2
	v_mov_b32_e32 v40, v2
	v_mov_b32_e32 v41, v2
	v_mov_b32_e32 v46, v2
	v_mov_b32_e32 v47, v2
	v_mov_b32_e32 v48, v2
	v_mov_b32_e32 v49, v2
	v_mov_b32_e32 v54, v2
	v_mov_b32_e32 v55, v2
	v_mov_b32_e32 v56, v2
	v_mov_b32_e32 v57, v2
	v_mov_b32_e32 v62, v2
	v_mov_b32_e32 v63, v2
	v_mov_b32_e32 v64, v2
	v_mov_b32_e32 v65, v2
	v_mov_b32_e32 v66, v2
	v_mov_b32_e32 v67, v2
	v_mov_b32_e32 v68, v2
	v_mov_b32_e32 v69, v2
	v_mov_b32_e32 v74, v2
	v_mov_b32_e32 v75, v2
	v_mov_b32_e32 v76, v2
	v_mov_b32_e32 v77, v2
	v_mov_b32_e32 v82, v2
	v_mov_b32_e32 v83, v2
	v_mov_b32_e32 v84, v2
	v_mov_b32_e32 v85, v2
	v_mov_b32_e32 v90, v2
	v_mov_b32_e32 v91, v2
	v_mov_b32_e32 v92, v2
	v_mov_b32_e32 v93, v2
	v_mov_b32_e32 v98, v2
	v_mov_b32_e32 v99, v2
	v_mov_b32_e32 v100, v2
	v_mov_b32_e32 v101, v2
	v_mov_b32_e32 v106, v2
	v_mov_b32_e32 v107, v2
	v_mov_b32_e32 v108, v2
	v_mov_b32_e32 v109, v2
	v_mov_b32_e32 v114, v2
	v_mov_b32_e32 v115, v2
	v_mov_b32_e32 v116, v2
	v_mov_b32_e32 v117, v2
	v_mov_b32_e32 v122, v2
	v_mov_b32_e32 v123, v2
	v_mov_b32_e32 v124, v2
	v_mov_b32_e32 v125, v2
	v_mov_b32_e32 v70, v2
	v_mov_b32_e32 v71, v2
	v_mov_b32_e32 v72, v2
	v_mov_b32_e32 v73, v2
	v_mov_b32_e32 v78, v2
	v_mov_b32_e32 v79, v2
	v_mov_b32_e32 v80, v2
	v_mov_b32_e32 v81, v2
	v_mov_b32_e32 v86, v2
	v_mov_b32_e32 v87, v2
	v_mov_b32_e32 v88, v2
	v_mov_b32_e32 v89, v2
	v_mov_b32_e32 v94, v2
	v_mov_b32_e32 v95, v2
	v_mov_b32_e32 v96, v2
	v_mov_b32_e32 v97, v2
	v_mov_b32_e32 v102, v2
	v_mov_b32_e32 v103, v2
	v_mov_b32_e32 v104, v2
	v_mov_b32_e32 v105, v2
	v_mov_b32_e32 v110, v2
	v_mov_b32_e32 v111, v2
	v_mov_b32_e32 v112, v2
	v_mov_b32_e32 v113, v2
	v_mov_b32_e32 v118, v2
	v_mov_b32_e32 v119, v2
	v_mov_b32_e32 v120, v2
	v_mov_b32_e32 v121, v2
	v_mov_b32_e32 v126, v2
	v_mov_b32_e32 v127, v2
	v_mov_b32_e32 v128, v2
	v_mov_b32_e32 v129, v2
	v_readlane_b32 s26, v253, 0
	s_nop 1
	s_cmp_eq_u32 s26, 0
	s_cbranch_scc1 .LBB0_283
	s_add_u32 s26, s22, 0xfffc0080
	s_addc_u32 s27, s23, -1
	s_add_i32 s69, 0, 0x10000
	s_cmp_eq_u32 s68, 12
	s_cselect_b32 s45, s30, s27
	s_cselect_b32 s44, s37, s26
	v_add_u32_e32 v156, s69, v152
	s_cselect_b32 s27, s13, s65
	s_cselect_b32 s26, s47, s56
	s_add_i32 s72, 0, 0x14000
	ds_read_b128 v[178:181], v156
	ds_read_b128 v[182:185], v156 offset:1024
	ds_read_b128 v[186:189], v156 offset:2048
	ds_read_b128 v[190:193], v156 offset:3072
	v_add_u32_e32 v156, s72, v152
	ds_read_b128 v[194:197], v156
	ds_read_b128 v[198:201], v156 offset:1024
	ds_read_b128 v[202:205], v156 offset:2048
	ds_read_b128 v[206:209], v156 offset:3072
	v_lshl_add_u64 v[156:157], s[22:23], 0, v[148:149]
	s_add_i32 m0, s50, 0xc000
	ds_read_b128 v[210:213], v155
	ds_read_b128 v[214:217], v155 offset:1024
	ds_read_b128 v[218:221], v155 offset:2048
	ds_read_b128 v[222:225], v155 offset:3072
	ds_read_b128 v[226:229], v155 offset:4096
	ds_read_b128 v[230:233], v155 offset:5120
	ds_read_b128 v[234:237], v155 offset:6144
	ds_read_b128 v[238:241], v155 offset:7168
	global_load_lds_dwordx4 v[156:157], off
	v_lshl_add_u64 v[156:157], s[22:23], 0, v[150:151]
	s_add_i32 m0, s50, 0xe000
	s_nop 0
	global_load_lds_dwordx4 v[156:157], off
	s_waitcnt vmcnt(16)
	s_waitcnt lgkmcnt(0)
	s_barrier
	s_setprio 1
	s_waitcnt lgkmcnt(0)
	v_mfma_f32_16x16x32_bf16 v[126:129], v[178:181], v[210:213], v[126:129]
	v_mfma_f32_16x16x32_bf16 v[118:121], v[186:189], v[210:213], v[118:121]
	v_mfma_f32_16x16x32_bf16 v[110:113], v[178:181], v[218:221], v[110:113]
	v_mfma_f32_16x16x32_bf16 v[102:105], v[186:189], v[218:221], v[102:105]
	v_mfma_f32_16x16x32_bf16 v[94:97], v[178:181], v[226:229], v[94:97]
	v_mfma_f32_16x16x32_bf16 v[86:89], v[186:189], v[226:229], v[86:89]
	v_mfma_f32_16x16x32_bf16 v[78:81], v[178:181], v[234:237], v[78:81]
	v_mfma_f32_16x16x32_bf16 v[70:73], v[186:189], v[234:237], v[70:73]
	v_mfma_f32_16x16x32_bf16 v[126:129], v[182:185], v[214:217], v[126:129]
	v_mfma_f32_16x16x32_bf16 v[118:121], v[190:193], v[214:217], v[118:121]
	v_mfma_f32_16x16x32_bf16 v[110:113], v[182:185], v[222:225], v[110:113]
	v_mfma_f32_16x16x32_bf16 v[102:105], v[190:193], v[222:225], v[102:105]
	v_mfma_f32_16x16x32_bf16 v[94:97], v[182:185], v[230:233], v[94:97]
	v_mfma_f32_16x16x32_bf16 v[86:89], v[190:193], v[230:233], v[86:89]
	v_mfma_f32_16x16x32_bf16 v[78:81], v[182:185], v[238:241], v[78:81]
	v_mfma_f32_16x16x32_bf16 v[70:73], v[190:193], v[238:241], v[70:73]
	s_setprio 0
	s_setprio 1
	v_mfma_f32_16x16x32_bf16 v[122:125], v[194:197], v[210:213], v[122:125]
	v_mfma_f32_16x16x32_bf16 v[114:117], v[202:205], v[210:213], v[114:117]
	v_mfma_f32_16x16x32_bf16 v[106:109], v[194:197], v[218:221], v[106:109]
	v_mfma_f32_16x16x32_bf16 v[98:101], v[202:205], v[218:221], v[98:101]
	v_mfma_f32_16x16x32_bf16 v[90:93], v[194:197], v[226:229], v[90:93]
	v_mfma_f32_16x16x32_bf16 v[82:85], v[202:205], v[226:229], v[82:85]
	v_mfma_f32_16x16x32_bf16 v[74:77], v[194:197], v[234:237], v[74:77]
	v_mfma_f32_16x16x32_bf16 v[66:69], v[202:205], v[234:237], v[66:69]
	v_mfma_f32_16x16x32_bf16 v[122:125], v[198:201], v[214:217], v[122:125]
	v_mfma_f32_16x16x32_bf16 v[114:117], v[206:209], v[214:217], v[114:117]
	v_mfma_f32_16x16x32_bf16 v[106:109], v[198:201], v[222:225], v[106:109]
	v_mfma_f32_16x16x32_bf16 v[98:101], v[206:209], v[222:225], v[98:101]
	s_setprio 2
	s_barrier
	v_mfma_f32_16x16x32_bf16 v[90:93], v[198:201], v[230:233], v[90:93]
	v_mfma_f32_16x16x32_bf16 v[82:85], v[206:209], v[230:233], v[82:85]
	v_mfma_f32_16x16x32_bf16 v[74:77], v[198:201], v[238:241], v[74:77]
	v_mfma_f32_16x16x32_bf16 v[66:69], v[206:209], v[238:241], v[66:69]
	s_setprio 0
	s_add_i32 s69, s69, s31
	v_lshl_add_u64 v[156:157], s[26:27], 0, v[134:135]
	s_mov_b32 m0, s69
	ds_read_b128 v[210:213], v155 offset:16384
	ds_read_b128 v[214:217], v155 offset:17408
	ds_read_b128 v[218:221], v155 offset:18432
	ds_read_b128 v[222:225], v155 offset:19456
	ds_read_b128 v[226:229], v155 offset:20480
	ds_read_b128 v[230:233], v155 offset:21504
	ds_read_b128 v[234:237], v155 offset:22528
	ds_read_b128 v[238:241], v155 offset:23552
	global_load_lds_dwordx4 v[156:157], off
	s_add_i32 m0, s69, 0x2000
	s_add_u32 s70, s26, 0x40000
	v_lshl_add_u64 v[160:161], s[26:27], 0, v[132:133]
	s_addc_u32 s71, s27, 0
	s_add_i32 s69, s72, s31
	global_load_lds_dwordx4 v[160:161], off
	v_lshl_add_u64 v[164:165], s[70:71], 0, v[134:135]
	s_mov_b32 m0, s69
	v_lshl_add_u64 v[242:243], s[44:45], 0, v[144:145]
	global_load_lds_dwordx4 v[164:165], off
	v_lshl_add_u64 v[164:165], s[70:71], 0, v[132:133]
	s_add_i32 m0, s69, 0x2000
	s_nop 0
	global_load_lds_dwordx4 v[164:165], off
	v_lshl_add_u64 v[164:165], s[44:45], 0, v[146:147]
	s_mov_b32 m0, s50
	s_nop 0
	global_load_lds_dwordx4 v[164:165], off
	s_mov_b32 m0, s51
	s_nop 0
	global_load_lds_dwordx4 v[242:243], off
	s_waitcnt vmcnt(16)
	s_waitcnt lgkmcnt(0)
	s_barrier
	s_setprio 1
	s_waitcnt lgkmcnt(0)
	v_mfma_f32_16x16x32_bf16 v[62:65], v[178:181], v[210:213], v[62:65]
	v_mfma_f32_16x16x32_bf16 v[54:57], v[186:189], v[210:213], v[54:57]
	v_mfma_f32_16x16x32_bf16 v[46:49], v[178:181], v[218:221], v[46:49]
	v_mfma_f32_16x16x32_bf16 v[38:41], v[186:189], v[218:221], v[38:41]
	v_mfma_f32_16x16x32_bf16 v[30:33], v[178:181], v[226:229], v[30:33]
	v_mfma_f32_16x16x32_bf16 v[22:25], v[186:189], v[226:229], v[22:25]
	v_mfma_f32_16x16x32_bf16 v[14:17], v[178:181], v[234:237], v[14:17]
	v_mfma_f32_16x16x32_bf16 v[6:9], v[186:189], v[234:237], v[6:9]
	v_mfma_f32_16x16x32_bf16 v[62:65], v[182:185], v[214:217], v[62:65]
	v_mfma_f32_16x16x32_bf16 v[54:57], v[190:193], v[214:217], v[54:57]
	v_mfma_f32_16x16x32_bf16 v[46:49], v[182:185], v[222:225], v[46:49]
	v_mfma_f32_16x16x32_bf16 v[38:41], v[190:193], v[222:225], v[38:41]
	v_mfma_f32_16x16x32_bf16 v[30:33], v[182:185], v[230:233], v[30:33]
	v_mfma_f32_16x16x32_bf16 v[22:25], v[190:193], v[230:233], v[22:25]
	v_mfma_f32_16x16x32_bf16 v[14:17], v[182:185], v[238:241], v[14:17]
	v_mfma_f32_16x16x32_bf16 v[6:9], v[190:193], v[238:241], v[6:9]
	s_setprio 0
	s_setprio 1
	v_mfma_f32_16x16x32_bf16 v[58:61], v[194:197], v[210:213], v[58:61]
	v_mfma_f32_16x16x32_bf16 v[50:53], v[202:205], v[210:213], v[50:53]
	v_mfma_f32_16x16x32_bf16 v[42:45], v[194:197], v[218:221], v[42:45]
	v_mfma_f32_16x16x32_bf16 v[34:37], v[202:205], v[218:221], v[34:37]
	v_mfma_f32_16x16x32_bf16 v[26:29], v[194:197], v[226:229], v[26:29]
	v_mfma_f32_16x16x32_bf16 v[18:21], v[202:205], v[226:229], v[18:21]
	v_mfma_f32_16x16x32_bf16 v[10:13], v[194:197], v[234:237], v[10:13]
	v_mfma_f32_16x16x32_bf16 v[2:5], v[202:205], v[234:237], v[2:5]
	v_mfma_f32_16x16x32_bf16 v[58:61], v[198:201], v[214:217], v[58:61]
	v_mfma_f32_16x16x32_bf16 v[50:53], v[206:209], v[214:217], v[50:53]
	v_mfma_f32_16x16x32_bf16 v[42:45], v[198:201], v[222:225], v[42:45]
	v_mfma_f32_16x16x32_bf16 v[34:37], v[206:209], v[222:225], v[34:37]
	s_setprio 2
	s_barrier
	v_mfma_f32_16x16x32_bf16 v[26:29], v[198:201], v[230:233], v[26:29]
	v_mfma_f32_16x16x32_bf16 v[18:21], v[206:209], v[230:233], v[18:21]
	v_mfma_f32_16x16x32_bf16 v[10:13], v[198:201], v[238:241], v[10:13]
	v_mfma_f32_16x16x32_bf16 v[2:5], v[206:209], v[238:241], v[2:5]
	s_setprio 0
	s_add_i32 s69, 0, 0x18000
	v_add_u32_e32 v159, s69, v152
	s_add_i32 s70, 0, 0x1c000
	ds_read_b128 v[178:181], v159
	ds_read_b128 v[182:185], v159 offset:1024
	ds_read_b128 v[186:189], v159 offset:2048
	ds_read_b128 v[190:193], v159 offset:3072
	v_add_u32_e32 v159, s70, v152
	ds_read_b128 v[194:197], v159
	ds_read_b128 v[198:201], v159 offset:1024
	ds_read_b128 v[202:205], v159 offset:2048
	ds_read_b128 v[206:209], v159 offset:3072
	s_add_u32 s44, s44, 0x40000
	s_addc_u32 s45, s45, 0
	s_mov_b32 m0, s52
	v_lshl_add_u64 v[244:245], s[44:45], 0, v[146:147]
	ds_read_b128 v[210:213], v155 offset:32768
	ds_read_b128 v[214:217], v155 offset:33792
	ds_read_b128 v[218:221], v155 offset:34816
	ds_read_b128 v[222:225], v155 offset:35840
	ds_read_b128 v[226:229], v155 offset:36864
	ds_read_b128 v[230:233], v155 offset:37888
	ds_read_b128 v[234:237], v155 offset:38912
	ds_read_b128 v[238:241], v155 offset:39936
	global_load_lds_dwordx4 v[244:245], off
	v_lshl_add_u64 v[244:245], s[44:45], 0, v[144:145]
	s_mov_b32 m0, s53
	s_nop 0
	global_load_lds_dwordx4 v[244:245], off
	s_waitcnt vmcnt(8)
	s_waitcnt lgkmcnt(0)
	s_barrier
	s_setprio 1
	s_waitcnt lgkmcnt(0)
	v_mfma_f32_16x16x32_bf16 v[126:129], v[178:181], v[210:213], v[126:129]
	v_mfma_f32_16x16x32_bf16 v[118:121], v[186:189], v[210:213], v[118:121]
	v_mfma_f32_16x16x32_bf16 v[110:113], v[178:181], v[218:221], v[110:113]
	v_mfma_f32_16x16x32_bf16 v[102:105], v[186:189], v[218:221], v[102:105]
	v_mfma_f32_16x16x32_bf16 v[94:97], v[178:181], v[226:229], v[94:97]
	v_mfma_f32_16x16x32_bf16 v[86:89], v[186:189], v[226:229], v[86:89]
	v_mfma_f32_16x16x32_bf16 v[78:81], v[178:181], v[234:237], v[78:81]
	v_mfma_f32_16x16x32_bf16 v[70:73], v[186:189], v[234:237], v[70:73]
	v_mfma_f32_16x16x32_bf16 v[126:129], v[182:185], v[214:217], v[126:129]
	v_mfma_f32_16x16x32_bf16 v[118:121], v[190:193], v[214:217], v[118:121]
	v_mfma_f32_16x16x32_bf16 v[110:113], v[182:185], v[222:225], v[110:113]
	v_mfma_f32_16x16x32_bf16 v[102:105], v[190:193], v[222:225], v[102:105]
	v_mfma_f32_16x16x32_bf16 v[94:97], v[182:185], v[230:233], v[94:97]
	v_mfma_f32_16x16x32_bf16 v[86:89], v[190:193], v[230:233], v[86:89]
	v_mfma_f32_16x16x32_bf16 v[78:81], v[182:185], v[238:241], v[78:81]
	v_mfma_f32_16x16x32_bf16 v[70:73], v[190:193], v[238:241], v[70:73]
	s_setprio 0
	s_setprio 1
	v_mfma_f32_16x16x32_bf16 v[122:125], v[194:197], v[210:213], v[122:125]
	v_mfma_f32_16x16x32_bf16 v[114:117], v[202:205], v[210:213], v[114:117]
	v_mfma_f32_16x16x32_bf16 v[106:109], v[194:197], v[218:221], v[106:109]
	v_mfma_f32_16x16x32_bf16 v[98:101], v[202:205], v[218:221], v[98:101]
	v_mfma_f32_16x16x32_bf16 v[90:93], v[194:197], v[226:229], v[90:93]
	v_mfma_f32_16x16x32_bf16 v[82:85], v[202:205], v[226:229], v[82:85]
	v_mfma_f32_16x16x32_bf16 v[74:77], v[194:197], v[234:237], v[74:77]
	v_mfma_f32_16x16x32_bf16 v[66:69], v[202:205], v[234:237], v[66:69]
	v_mfma_f32_16x16x32_bf16 v[122:125], v[198:201], v[214:217], v[122:125]
	v_mfma_f32_16x16x32_bf16 v[114:117], v[206:209], v[214:217], v[114:117]
	v_mfma_f32_16x16x32_bf16 v[106:109], v[198:201], v[222:225], v[106:109]
	v_mfma_f32_16x16x32_bf16 v[98:101], v[206:209], v[222:225], v[98:101]
	s_setprio 2
	s_barrier
	v_mfma_f32_16x16x32_bf16 v[90:93], v[198:201], v[230:233], v[90:93]
	v_mfma_f32_16x16x32_bf16 v[82:85], v[206:209], v[230:233], v[82:85]
	v_mfma_f32_16x16x32_bf16 v[74:77], v[198:201], v[238:241], v[74:77]
	v_mfma_f32_16x16x32_bf16 v[66:69], v[206:209], v[238:241], v[66:69]
	s_setprio 0
	s_add_i32 s44, s69, s31
	v_lshl_add_u64 v[156:157], v[156:157], 0, s[66:67]
	s_mov_b32 m0, s44
	ds_read_b128 v[210:213], v155 offset:49152
	ds_read_b128 v[214:217], v155 offset:50176
	ds_read_b128 v[218:221], v155 offset:51200
	ds_read_b128 v[222:225], v155 offset:52224
	ds_read_b128 v[226:229], v155 offset:53248
	ds_read_b128 v[230:233], v155 offset:54272
	ds_read_b128 v[234:237], v155 offset:55296
	ds_read_b128 v[238:241], v155 offset:56320
	global_load_lds_dwordx4 v[156:157], off
	s_add_i32 m0, s44, 0x2000
	s_add_u32 s26, s26, 0x40080
	v_lshl_add_u64 v[156:157], v[160:161], 0, s[66:67]
	s_addc_u32 s27, s27, 0
	s_add_i32 s44, s70, s31
	global_load_lds_dwordx4 v[156:157], off
	v_lshl_add_u64 v[156:157], s[26:27], 0, v[134:135]
	s_mov_b32 m0, s44
	s_nop 0
	global_load_lds_dwordx4 v[156:157], off
	v_lshl_add_u64 v[156:157], s[26:27], 0, v[132:133]
	s_add_i32 m0, s44, 0x2000
	s_nop 0
	global_load_lds_dwordx4 v[156:157], off
	v_lshl_add_u64 v[156:157], v[164:165], 0, s[66:67]
	s_mov_b32 m0, s19
	s_nop 0
	global_load_lds_dwordx4 v[156:157], off
	v_lshl_add_u64 v[156:157], v[242:243], 0, s[66:67]
	s_mov_b32 m0, s60
	s_nop 0
	global_load_lds_dwordx4 v[156:157], off
	s_waitcnt vmcnt(8)
	s_waitcnt lgkmcnt(0)
	s_barrier
	s_setprio 1
	s_waitcnt lgkmcnt(0)
	v_mfma_f32_16x16x32_bf16 v[62:65], v[178:181], v[210:213], v[62:65]
	v_mfma_f32_16x16x32_bf16 v[54:57], v[186:189], v[210:213], v[54:57]
	v_mfma_f32_16x16x32_bf16 v[46:49], v[178:181], v[218:221], v[46:49]
	v_mfma_f32_16x16x32_bf16 v[38:41], v[186:189], v[218:221], v[38:41]
	v_mfma_f32_16x16x32_bf16 v[30:33], v[178:181], v[226:229], v[30:33]
	v_mfma_f32_16x16x32_bf16 v[22:25], v[186:189], v[226:229], v[22:25]
	v_mfma_f32_16x16x32_bf16 v[14:17], v[178:181], v[234:237], v[14:17]
	v_mfma_f32_16x16x32_bf16 v[6:9], v[186:189], v[234:237], v[6:9]
	v_mfma_f32_16x16x32_bf16 v[62:65], v[182:185], v[214:217], v[62:65]
	v_mfma_f32_16x16x32_bf16 v[54:57], v[190:193], v[214:217], v[54:57]
	v_mfma_f32_16x16x32_bf16 v[46:49], v[182:185], v[222:225], v[46:49]
	v_mfma_f32_16x16x32_bf16 v[38:41], v[190:193], v[222:225], v[38:41]
	v_mfma_f32_16x16x32_bf16 v[30:33], v[182:185], v[230:233], v[30:33]
	v_mfma_f32_16x16x32_bf16 v[22:25], v[190:193], v[230:233], v[22:25]
	v_mfma_f32_16x16x32_bf16 v[14:17], v[182:185], v[238:241], v[14:17]
	v_mfma_f32_16x16x32_bf16 v[6:9], v[190:193], v[238:241], v[6:9]
	s_setprio 0
	s_setprio 1
	v_mfma_f32_16x16x32_bf16 v[58:61], v[194:197], v[210:213], v[58:61]
	v_mfma_f32_16x16x32_bf16 v[50:53], v[202:205], v[210:213], v[50:53]
	v_mfma_f32_16x16x32_bf16 v[42:45], v[194:197], v[218:221], v[42:45]
	v_mfma_f32_16x16x32_bf16 v[34:37], v[202:205], v[218:221], v[34:37]
	v_mfma_f32_16x16x32_bf16 v[26:29], v[194:197], v[226:229], v[26:29]
	v_mfma_f32_16x16x32_bf16 v[18:21], v[202:205], v[226:229], v[18:21]
	v_mfma_f32_16x16x32_bf16 v[10:13], v[194:197], v[234:237], v[10:13]
	v_mfma_f32_16x16x32_bf16 v[2:5], v[202:205], v[234:237], v[2:5]
	v_mfma_f32_16x16x32_bf16 v[58:61], v[198:201], v[214:217], v[58:61]
	v_mfma_f32_16x16x32_bf16 v[50:53], v[206:209], v[214:217], v[50:53]
	v_mfma_f32_16x16x32_bf16 v[42:45], v[198:201], v[222:225], v[42:45]
	v_mfma_f32_16x16x32_bf16 v[34:37], v[206:209], v[222:225], v[34:37]
	s_setprio 2
	s_barrier
	v_mfma_f32_16x16x32_bf16 v[26:29], v[198:201], v[230:233], v[26:29]
	v_mfma_f32_16x16x32_bf16 v[18:21], v[206:209], v[230:233], v[18:21]
	v_mfma_f32_16x16x32_bf16 v[10:13], v[198:201], v[238:241], v[10:13]
	v_mfma_f32_16x16x32_bf16 v[2:5], v[206:209], v[238:241], v[2:5]
	s_setprio 0
	s_add_i32 s68, s68, 2
	s_add_u32 s22, s22, 0x100
	s_addc_u32 s23, s23, 0
	s_add_u32 s56, s56, 0x100
	s_addc_u32 s65, s65, 0
	s_cmp_gt_u32 s68, 13
